# code placement: .p2align 6 in front of the 7 GEMM K-loop heads (64-byte aligned loop heads)
# speedup vs baseline: 1.0145x; 1.0145x over previous
; template <class Epi, class Sched, bool ALIGN_EPI = false, bool SP2 = false, bool A_TILED = false, bool B_TILED = false>
; __device__ __forceinline__ void gemm_phase(PG8_LAS unsigned char* lds, const Gemm g, const Sched& S, const Epi& E) {
;     ...
;         const char* nA = has_next ? (const char*)g.A + (size_t)nxt.pm * tstep + (size_t)nxt.kt0 * kstepA : cA; const char* nB = has_next ? (const char*)g.Bt + (size_t)nxt.pn * tstep + (size_t)nxt.kt0 * kstepB : cB;
;         for (int t = 0; t < nt; t += 2) {
;             const bool last = (t == nt - 2);
;             const char* a1 = cA + (size_t)(t + 1) * kstepA;
;             const char* a2 = last ? nA : cA + (size_t)(t + 2) * kstepA; const char* b2 = last ? nB : cB + (size_t)(t + 2) * kstepB;
;     ...
; #pragma unroll
;         for (int a = 0; a < 2; ++a)
; #pragma unroll
;             for (int b = 0; b < 2; ++b)
; #pragma unroll
;                 for (int m = 0; m < 4; ++m)
; #pragma unroll
;                     for (int n = 0; n < 2; ++n) acc[a][b][m][n] = (f32x4){0.f, 0.f, 0.f, 0.f};
.LBB0_101:
	s_mov_b32 s20, s21
	s_ashr_i32 s21, s21, 31
	s_lshl_b64 s[28:29], s[20:21], 21
	s_add_u32 s28, s33, s28
	s_addc_u32 s29, s40, s29
	s_mov_b32 s18, s23
	s_and_b64 s[30:31], s[26:27], exec
	s_cselect_b32 s21, s29, s35
	s_cselect_b32 s23, s28, s34
	s_ashr_i32 s19, s18, 31
	s_lshl_b64 s[30:31], s[18:19], 21
	s_add_u32 s30, s41, s30
	s_addc_u32 s31, s42, s31
	s_and_b64 s[38:39], s[26:27], exec
	s_cselect_b32 s19, s31, s37
	s_cselect_b32 s65, s30, s36
	s_add_u32 s34, s34, 0x100080
	s_addc_u32 s35, s35, 0
	s_add_u32 s66, s36, 0x100
	v_mov_b32_e32 v2, 0
	s_addc_u32 s67, s37, 0
	s_mov_b32 s68, -2
	v_mov_b32_e32 v3, v2
	v_mov_b32_e32 v4, v2
	v_mov_b32_e32 v5, v2
	v_mov_b32_e32 v6, v2
	v_mov_b32_e32 v7, v2
	v_mov_b32_e32 v8, v2
	v_mov_b32_e32 v9, v2
	v_mov_b32_e32 v10, v2
	v_mov_b32_e32 v11, v2
	v_mov_b32_e32 v12, v2
	v_mov_b32_e32 v13, v2
	v_mov_b32_e32 v18, v2
	v_mov_b32_e32 v19, v2
	v_mov_b32_e32 v20, v2
	v_mov_b32_e32 v21, v2
	v_mov_b32_e32 v26, v2
	v_mov_b32_e32 v27, v2
	v_mov_b32_e32 v28, v2
	v_mov_b32_e32 v29, v2
	v_mov_b32_e32 v34, v2
	v_mov_b32_e32 v35, v2
	v_mov_b32_e32 v36, v2
	v_mov_b32_e32 v37, v2
	v_mov_b32_e32 v42, v2
	v_mov_b32_e32 v43, v2
	v_mov_b32_e32 v44, v2
	v_mov_b32_e32 v45, v2
	v_mov_b32_e32 v50, v2
	v_mov_b32_e32 v51, v2
	v_mov_b32_e32 v52, v2
	v_mov_b32_e32 v53, v2
	v_mov_b32_e32 v14, v2
	v_mov_b32_e32 v15, v2
	v_mov_b32_e32 v16, v2
	v_mov_b32_e32 v17, v2
	v_mov_b32_e32 v22, v2
	v_mov_b32_e32 v23, v2
	v_mov_b32_e32 v24, v2
	v_mov_b32_e32 v25, v2
	v_mov_b32_e32 v30, v2
	v_mov_b32_e32 v31, v2
	v_mov_b32_e32 v32, v2
	v_mov_b32_e32 v33, v2
	v_mov_b32_e32 v38, v2
	v_mov_b32_e32 v39, v2
	v_mov_b32_e32 v40, v2
	v_mov_b32_e32 v41, v2
	v_mov_b32_e32 v46, v2
	v_mov_b32_e32 v47, v2
	v_mov_b32_e32 v48, v2
	v_mov_b32_e32 v49, v2
	v_mov_b32_e32 v54, v2
	v_mov_b32_e32 v55, v2
	v_mov_b32_e32 v56, v2
	v_mov_b32_e32 v57, v2
	v_mov_b32_e32 v58, v2
	v_mov_b32_e32 v59, v2
	v_mov_b32_e32 v60, v2
	v_mov_b32_e32 v61, v2
	v_mov_b32_e32 v62, v2
	v_mov_b32_e32 v63, v2
	v_mov_b32_e32 v64, v2
	v_mov_b32_e32 v65, v2
	v_mov_b32_e32 v66, v2
	v_mov_b32_e32 v67, v2
	v_mov_b32_e32 v68, v2
	v_mov_b32_e32 v69, v2
	v_mov_b32_e32 v70, v2
	v_mov_b32_e32 v71, v2
	v_mov_b32_e32 v72, v2
	v_mov_b32_e32 v73, v2
	v_mov_b32_e32 v74, v2
	v_mov_b32_e32 v75, v2
	v_mov_b32_e32 v76, v2
	v_mov_b32_e32 v77, v2
	v_mov_b32_e32 v82, v2
	v_mov_b32_e32 v83, v2
	v_mov_b32_e32 v84, v2
	v_mov_b32_e32 v85, v2
	v_mov_b32_e32 v90, v2
	v_mov_b32_e32 v91, v2
	v_mov_b32_e32 v92, v2
	v_mov_b32_e32 v93, v2
	v_mov_b32_e32 v98, v2
	v_mov_b32_e32 v99, v2
	v_mov_b32_e32 v100, v2
	v_mov_b32_e32 v101, v2
	v_mov_b32_e32 v106, v2
	v_mov_b32_e32 v107, v2
	v_mov_b32_e32 v108, v2
	v_mov_b32_e32 v109, v2
	v_mov_b32_e32 v114, v2
	v_mov_b32_e32 v115, v2
	v_mov_b32_e32 v116, v2
	v_mov_b32_e32 v117, v2
	v_mov_b32_e32 v78, v2
	v_mov_b32_e32 v79, v2
	v_mov_b32_e32 v80, v2
	v_mov_b32_e32 v81, v2
	v_mov_b32_e32 v86, v2
	v_mov_b32_e32 v87, v2
	v_mov_b32_e32 v88, v2
	v_mov_b32_e32 v89, v2
	v_mov_b32_e32 v94, v2
	v_mov_b32_e32 v95, v2
	v_mov_b32_e32 v96, v2
	v_mov_b32_e32 v97, v2
	v_mov_b32_e32 v102, v2
	v_mov_b32_e32 v103, v2
	v_mov_b32_e32 v104, v2
	v_mov_b32_e32 v105, v2
	v_mov_b32_e32 v110, v2
	v_mov_b32_e32 v111, v2
	v_mov_b32_e32 v112, v2
	v_mov_b32_e32 v113, v2
	v_mov_b32_e32 v118, v2
	v_mov_b32_e32 v119, v2
	v_mov_b32_e32 v120, v2
	v_mov_b32_e32 v121, v2
	v_mov_b32_e32 v122, v2
	v_mov_b32_e32 v123, v2
	v_mov_b32_e32 v124, v2
	v_mov_b32_e32 v125, v2
	v_mov_b32_e32 v126, v2
	v_mov_b32_e32 v127, v2
	v_mov_b32_e32 v128, v2
	v_mov_b32_e32 v129, v2
	.p2align	6

; template <class Epi, class Sched, bool ALIGN_EPI = false, bool SP2 = false, bool A_TILED = false, bool B_TILED = false>
; __device__ __forceinline__ void gemm_phase(PG8_LAS unsigned char* lds, const Gemm g, const Sched& S, const Epi& E) {
;     ...
;         const char* nA = has_next ? (const char*)g.A + (size_t)nxt.pm * tstep + (size_t)nxt.kt0 * kstepA : cA; const char* nB = has_next ? (const char*)g.Bt + (size_t)nxt.pn * tstep + (size_t)nxt.kt0 * kstepB : cB;
;         for (int t = 0; t < nt; t += 2) {
;             const bool last = (t == nt - 2);
;             const char* a1 = cA + (size_t)(t + 1) * kstepA;
;             const char* a2 = last ? nA : cA + (size_t)(t + 2) * kstepA; const char* b2 = last ? nB : cB + (size_t)(t + 2) * kstepB;
.LBB0_512:
	s_ashr_i32 s37, s36, 31
	s_lshl_b64 s[38:39], s[36:37], 21
	s_add_u32 s11, s33, s38
	s_addc_u32 s31, s46, s39
	s_ashr_i32 s35, s34, 31
	s_lshl_b64 s[40:41], s[34:35], 7
	s_add_u32 s38, s11, s40
	s_addc_u32 s39, s31, s41
	s_and_b64 s[44:45], s[6:7], exec
	s_cselect_b32 s11, s39, s13
	s_cselect_b32 s35, s38, s12
	s_ashr_i32 s31, s30, 31
	s_lshl_b64 s[44:45], s[30:31], 21
	s_add_u32 s31, s47, s44
	s_addc_u32 s37, s52, s45
	s_add_u32 s40, s31, s40
	s_addc_u32 s41, s37, s41
	s_and_b64 s[44:45], s[6:7], exec
	s_cselect_b32 s31, s41, s43
	s_cselect_b32 s37, s40, s42
	s_add_u32 s12, s12, 0x100080
	s_addc_u32 s13, s13, 0
	s_add_u32 s66, s42, 0x100
	s_addc_u32 s67, s43, 0
	s_mov_b32 s68, -2
	.p2align	6

; template <class Epi, class Sched, bool ALIGN_EPI = false, bool SP2 = false, bool A_TILED = false, bool B_TILED = false>
; __device__ __forceinline__ void gemm_phase(PG8_LAS unsigned char* lds, const Gemm g, const Sched& S, const Epi& E) {
;     ...
;         const char* nA = has_next ? (const char*)g.A + (size_t)nxt.pm * tstep + (size_t)nxt.kt0 * kstepA : cA; const char* nB = has_next ? (const char*)g.Bt + (size_t)nxt.pn * tstep + (size_t)nxt.kt0 * kstepB : cB;
;         for (int t = 0; t < nt; t += 2) {
;             const bool last = (t == nt - 2);
;             const char* a1 = cA + (size_t)(t + 1) * kstepA;
;             const char* a2 = last ? nA : cA + (size_t)(t + 2) * kstepA; const char* b2 = last ? nB : cB + (size_t)(t + 2) * kstepB;
;     ...
; #pragma unroll
;         for (int a = 0; a < 2; ++a)
; #pragma unroll
;             for (int b = 0; b < 2; ++b)
; #pragma unroll
;                 for (int m = 0; m < 4; ++m)
; #pragma unroll
;                     for (int n = 0; n < 2; ++n) acc[a][b][m][n] = (f32x4){0.f, 0.f, 0.f, 0.f};
.LBB0_552:
	s_ashr_i32 s25, s24, 31
	s_lshl_b64 s[30:31], s[24:25], 21
	s_add_u32 s5, s33, s30
	s_addc_u32 s7, s46, s31
	s_ashr_i32 s27, s26, 31
	s_lshl_b64 s[34:35], s[26:27], 7
	s_add_u32 s30, s5, s34
	s_addc_u32 s31, s7, s35
	s_and_b64 s[40:41], s[28:29], exec
	s_cselect_b32 s5, s31, s37
	s_cselect_b32 s7, s30, s36
	s_ashr_i32 s23, s22, 31
	s_lshl_b64 s[40:41], s[22:23], 21
	s_add_u32 s23, s47, s40
	s_addc_u32 s25, s52, s41
	s_add_u32 s34, s23, s34
	s_addc_u32 s35, s25, s35
	s_and_b64 s[40:41], s[28:29], exec
	s_cselect_b32 s23, s35, s39
	s_cselect_b32 s25, s34, s38
	s_add_u32 s36, s36, 0x100080
	s_addc_u32 s37, s37, 0
	s_add_u32 s27, s38, 0x100
	v_mov_b32_e32 v2, 0
	s_addc_u32 s58, s39, 0
	s_mov_b32 s59, -2
	v_mov_b32_e32 v3, v2
	v_mov_b32_e32 v4, v2
	v_mov_b32_e32 v5, v2
	v_mov_b32_e32 v6, v2
	v_mov_b32_e32 v7, v2
	v_mov_b32_e32 v8, v2
	v_mov_b32_e32 v9, v2
	v_mov_b32_e32 v18, v2
	v_mov_b32_e32 v19, v2
	v_mov_b32_e32 v20, v2
	v_mov_b32_e32 v21, v2
	v_mov_b32_e32 v22, v2
	v_mov_b32_e32 v23, v2
	v_mov_b32_e32 v24, v2
	v_mov_b32_e32 v25, v2
	v_mov_b32_e32 v34, v2
	v_mov_b32_e32 v35, v2
	v_mov_b32_e32 v36, v2
	v_mov_b32_e32 v37, v2
	v_mov_b32_e32 v38, v2
	v_mov_b32_e32 v39, v2
	v_mov_b32_e32 v40, v2
	v_mov_b32_e32 v41, v2
	s_waitcnt vmcnt(0)
	v_mov_b32_e32 v50, v2
	v_mov_b32_e32 v51, v2
	v_mov_b32_e32 v52, v2
	v_mov_b32_e32 v53, v2
	v_mov_b32_e32 v54, v2
	v_mov_b32_e32 v55, v2
	v_mov_b32_e32 v56, v2
	v_mov_b32_e32 v57, v2
	v_mov_b32_e32 v10, v2
	v_mov_b32_e32 v11, v2
	v_mov_b32_e32 v12, v2
	v_mov_b32_e32 v13, v2
	v_mov_b32_e32 v14, v2
	v_mov_b32_e32 v15, v2
	v_mov_b32_e32 v16, v2
	v_mov_b32_e32 v17, v2
	v_mov_b32_e32 v26, v2
	v_mov_b32_e32 v27, v2
	v_mov_b32_e32 v28, v2
	v_mov_b32_e32 v29, v2
	v_mov_b32_e32 v30, v2
	v_mov_b32_e32 v31, v2
	v_mov_b32_e32 v32, v2
	v_mov_b32_e32 v33, v2
	v_mov_b32_e32 v42, v2
	v_mov_b32_e32 v43, v2
	v_mov_b32_e32 v44, v2
	v_mov_b32_e32 v45, v2
	v_mov_b32_e32 v46, v2
	v_mov_b32_e32 v47, v2
	v_mov_b32_e32 v48, v2
	v_mov_b32_e32 v49, v2
	v_mov_b32_e32 v58, v2
	v_mov_b32_e32 v59, v2
	v_mov_b32_e32 v60, v2
	v_mov_b32_e32 v61, v2
	v_mov_b32_e32 v62, v2
	v_mov_b32_e32 v63, v2
	v_mov_b32_e32 v64, v2
	v_mov_b32_e32 v65, v2
	v_mov_b32_e32 v66, v2
	v_mov_b32_e32 v67, v2
	v_mov_b32_e32 v68, v2
	v_mov_b32_e32 v69, v2
	v_mov_b32_e32 v70, v2
	v_mov_b32_e32 v71, v2
	v_mov_b32_e32 v72, v2
	v_mov_b32_e32 v73, v2
	v_mov_b32_e32 v82, v2
	v_mov_b32_e32 v83, v2
	v_mov_b32_e32 v84, v2
	v_mov_b32_e32 v85, v2
	v_mov_b32_e32 v86, v2
	v_mov_b32_e32 v87, v2
	v_mov_b32_e32 v88, v2
	v_mov_b32_e32 v89, v2
	v_mov_b32_e32 v98, v2
	v_mov_b32_e32 v99, v2
	v_mov_b32_e32 v100, v2
	v_mov_b32_e32 v101, v2
	v_mov_b32_e32 v102, v2
	v_mov_b32_e32 v103, v2
	v_mov_b32_e32 v104, v2
	v_mov_b32_e32 v105, v2
	v_mov_b32_e32 v114, v2
	v_mov_b32_e32 v115, v2
	v_mov_b32_e32 v116, v2
	v_mov_b32_e32 v117, v2
	v_mov_b32_e32 v118, v2
	v_mov_b32_e32 v119, v2
	v_mov_b32_e32 v120, v2
	v_mov_b32_e32 v121, v2
	v_mov_b32_e32 v74, v2
	v_mov_b32_e32 v75, v2
	v_mov_b32_e32 v76, v2
	v_mov_b32_e32 v77, v2
	v_mov_b32_e32 v78, v2
	v_mov_b32_e32 v79, v2
	v_mov_b32_e32 v80, v2
	v_mov_b32_e32 v81, v2
	v_mov_b32_e32 v90, v2
	v_mov_b32_e32 v91, v2
	v_mov_b32_e32 v92, v2
	v_mov_b32_e32 v93, v2
	v_mov_b32_e32 v94, v2
	v_mov_b32_e32 v95, v2
	v_mov_b32_e32 v96, v2
	v_mov_b32_e32 v97, v2
	v_mov_b32_e32 v106, v2
	v_mov_b32_e32 v107, v2
	v_mov_b32_e32 v108, v2
	v_mov_b32_e32 v109, v2
	v_mov_b32_e32 v110, v2
	v_mov_b32_e32 v111, v2
	v_mov_b32_e32 v112, v2
	v_mov_b32_e32 v113, v2
	v_mov_b32_e32 v122, v2
	v_mov_b32_e32 v123, v2
	v_mov_b32_e32 v124, v2
	v_mov_b32_e32 v125, v2
	v_mov_b32_e32 v126, v2
	v_mov_b32_e32 v127, v2
	v_mov_b32_e32 v128, v2
	v_mov_b32_e32 v129, v2
	.p2align	6

; #define PG8_LAS __attribute__((address_space(3)))
;     __device__ __forceinline__ void operator()(const f32x4 (&acc)[2][2][4][2], const Unit& u, int wr, int wc, int fr, int fq) const {
;     ...
;           else { const int wv_ = __builtin_amdgcn_readfirstlane(tid_ >> 6) - 4; int l2_ = 2 * (tid_ & 63); asm volatile("" : "+v"(l2_));
;                  const float* src_ = ((wv_ == 3) ? cb : cw + (size_t)wv_ * DFF) + u.pn * 128; typedef float f32x2e __attribute__((ext_vector_type(2)));
;                  *(PG8_LAS f32x2e*)(T + wv_ * 128 + l2_) = *(const f32x2e*)(src_ + l2_); } }
.Lg3h_w7:
	s_lshl_b32 vcc_lo, s6, 9
	s_add_u32 s100, s100, vcc_lo
	s_addc_u32 s101, s101, 0
	v_mov_b32_e32 v252, v204
	v_ashrrev_i32_e32 v253, 31, v204
	v_lshl_add_u64 v[252:253], v[252:253], 2, s[100:101]
	global_load_dwordx2 v[246:247], v[252:253], off
	.p2align	6

; template <class Epi, class Sched, bool ALIGN_EPI = false, bool SP2 = false, bool A_TILED = false, bool B_TILED = false>
; __device__ __forceinline__ void gemm_phase(PG8_LAS unsigned char* lds, const Gemm g, const Sched& S, const Epi& E) {
;     ...
;         const char* nA = has_next ? (const char*)g.A + (size_t)nxt.pm * tstep + (size_t)nxt.kt0 * kstepA : cA; const char* nB = has_next ? (const char*)g.Bt + (size_t)nxt.pn * tstep + (size_t)nxt.kt0 * kstepB : cB;
;         for (int t = 0; t < nt; t += 2) {
;             const bool last = (t == nt - 2);
;             const char* a1 = cA + (size_t)(t + 1) * kstepA;
;             const char* a2 = last ? nA : cA + (size_t)(t + 2) * kstepA; const char* b2 = last ? nB : cB + (size_t)(t + 2) * kstepB;
;     ...
; #pragma unroll
;         for (int a = 0; a < 2; ++a)
; #pragma unroll
;             for (int b = 0; b < 2; ++b)
; #pragma unroll
;                 for (int m = 0; m < 4; ++m)
; #pragma unroll
;                     for (int n = 0; n < 2; ++n) acc[a][b][m][n] = (f32x4){0.f, 0.f, 0.f, 0.f};
.LBB0_904:
	s_ashr_i32 s13, s12, 31
	s_lshl_b64 s[20:21], s[12:13], 21
	s_add_u32 s13, s88, s20
	s_addc_u32 s15, s89, s21
	s_ashr_i32 s17, s16, 31
	s_lshl_b64 s[22:23], s[16:17], 7
	s_add_u32 s20, s13, s22
	s_addc_u32 s21, s15, s23
	s_and_b64 s[34:35], s[18:19], exec
	s_cselect_b32 s13, s21, s27
	s_cselect_b32 s17, s20, s26
	s_ashr_i32 s15, s14, 31
	s_lshl_b64 s[34:35], s[14:15], 21
	s_add_u32 s15, s90, s34
	s_addc_u32 s25, s91, s35
	s_add_u32 s22, s15, s22
	s_addc_u32 s23, s25, s23
	s_and_b64 s[34:35], s[18:19], exec
	s_cselect_b32 s15, s23, s31
	s_cselect_b32 s25, s22, s30
	s_add_u32 s26, s26, 0x100080
	s_addc_u32 s27, s27, 0
	s_add_u32 s42, s30, 0x100
	v_mov_b32_e32 v2, 0
	s_addc_u32 s43, s31, 0
	s_mov_b32 s44, -2
	v_mov_b32_e32 v3, v2
	v_mov_b32_e32 v4, v2
	v_mov_b32_e32 v5, v2
	v_mov_b32_e32 v6, v2
	v_mov_b32_e32 v7, v2
	v_mov_b32_e32 v8, v2
	v_mov_b32_e32 v9, v2
	v_mov_b32_e32 v10, v2
	v_mov_b32_e32 v11, v2
	v_mov_b32_e32 v12, v2
	v_mov_b32_e32 v13, v2
	v_mov_b32_e32 v14, v2
	v_mov_b32_e32 v15, v2
	v_mov_b32_e32 v16, v2
	v_mov_b32_e32 v17, v2
	v_mov_b32_e32 v18, v2
	v_mov_b32_e32 v19, v2
	v_mov_b32_e32 v20, v2
	v_mov_b32_e32 v21, v2
	v_mov_b32_e32 v26, v2
	v_mov_b32_e32 v27, v2
	v_mov_b32_e32 v28, v2
	v_mov_b32_e32 v29, v2
	v_mov_b32_e32 v34, v2
	v_mov_b32_e32 v35, v2
	v_mov_b32_e32 v36, v2
	v_mov_b32_e32 v37, v2
	v_mov_b32_e32 v42, v2
	v_mov_b32_e32 v43, v2
	v_mov_b32_e32 v44, v2
	v_mov_b32_e32 v45, v2
	v_mov_b32_e32 v22, v2
	v_mov_b32_e32 v23, v2
	v_mov_b32_e32 v24, v2
	v_mov_b32_e32 v25, v2
	v_mov_b32_e32 v30, v2
	v_mov_b32_e32 v31, v2
	v_mov_b32_e32 v32, v2
	v_mov_b32_e32 v33, v2
	v_mov_b32_e32 v38, v2
	v_mov_b32_e32 v39, v2
	v_mov_b32_e32 v40, v2
	v_mov_b32_e32 v41, v2
	v_mov_b32_e32 v46, v2
	v_mov_b32_e32 v47, v2
	v_mov_b32_e32 v48, v2
	v_mov_b32_e32 v49, v2
	v_mov_b32_e32 v50, v2
	v_mov_b32_e32 v51, v2
	v_mov_b32_e32 v52, v2
	v_mov_b32_e32 v53, v2
	v_mov_b32_e32 v54, v2
	v_mov_b32_e32 v55, v2
	v_mov_b32_e32 v56, v2
	v_mov_b32_e32 v57, v2
	v_mov_b32_e32 v58, v2
	v_mov_b32_e32 v59, v2
	v_mov_b32_e32 v60, v2
	v_mov_b32_e32 v61, v2
	v_mov_b32_e32 v62, v2
	v_mov_b32_e32 v63, v2
	v_mov_b32_e32 v64, v2
	v_mov_b32_e32 v65, v2
	v_mov_b32_e32 v66, v2
	v_mov_b32_e32 v67, v2
	v_mov_b32_e32 v68, v2
	v_mov_b32_e32 v69, v2
	v_mov_b32_e32 v70, v2
	v_mov_b32_e32 v71, v2
	v_mov_b32_e32 v72, v2
	v_mov_b32_e32 v73, v2
	v_mov_b32_e32 v74, v2
	v_mov_b32_e32 v75, v2
	v_mov_b32_e32 v76, v2
	v_mov_b32_e32 v77, v2
	v_mov_b32_e32 v78, v2
	v_mov_b32_e32 v79, v2
	v_mov_b32_e32 v80, v2
	v_mov_b32_e32 v81, v2
	v_mov_b32_e32 v82, v2
	v_mov_b32_e32 v83, v2
	v_mov_b32_e32 v84, v2
	v_mov_b32_e32 v85, v2
	v_mov_b32_e32 v90, v2
	v_mov_b32_e32 v91, v2
	v_mov_b32_e32 v92, v2
	v_mov_b32_e32 v93, v2
	v_mov_b32_e32 v98, v2
	v_mov_b32_e32 v99, v2
	v_mov_b32_e32 v100, v2
	v_mov_b32_e32 v101, v2
	v_mov_b32_e32 v106, v2
	v_mov_b32_e32 v107, v2
	v_mov_b32_e32 v108, v2
	v_mov_b32_e32 v109, v2
	v_mov_b32_e32 v86, v2
	v_mov_b32_e32 v87, v2
	v_mov_b32_e32 v88, v2
	v_mov_b32_e32 v89, v2
	v_mov_b32_e32 v94, v2
	v_mov_b32_e32 v95, v2
	v_mov_b32_e32 v96, v2
	v_mov_b32_e32 v97, v2
	v_mov_b32_e32 v102, v2
	v_mov_b32_e32 v103, v2
	v_mov_b32_e32 v104, v2
	v_mov_b32_e32 v105, v2
	v_mov_b32_e32 v110, v2
	v_mov_b32_e32 v111, v2
	v_mov_b32_e32 v112, v2
	v_mov_b32_e32 v113, v2
	v_mov_b32_e32 v114, v2
	v_mov_b32_e32 v115, v2
	v_mov_b32_e32 v116, v2
	v_mov_b32_e32 v117, v2
	v_mov_b32_e32 v118, v2
	v_mov_b32_e32 v119, v2
	v_mov_b32_e32 v120, v2
	v_mov_b32_e32 v121, v2
	v_mov_b32_e32 v122, v2
	v_mov_b32_e32 v123, v2
	v_mov_b32_e32 v124, v2
	v_mov_b32_e32 v125, v2
	v_mov_b32_e32 v126, v2
	v_mov_b32_e32 v127, v2
	v_mov_b32_e32 v128, v2
	v_mov_b32_e32 v129, v2
	.p2align	6

; template <class Epi, class Sched, bool ALIGN_EPI = false, bool SP2 = false, bool A_TILED = false, bool B_TILED = false>
; __device__ __forceinline__ void gemm_phase(PG8_LAS unsigned char* lds, const Gemm g, const Sched& S, const Epi& E) {
;     ...
;         const char* nA = has_next ? (const char*)g.A + (size_t)nxt.pm * tstep + (size_t)nxt.kt0 * kstepA : cA; const char* nB = has_next ? (const char*)g.Bt + (size_t)nxt.pn * tstep + (size_t)nxt.kt0 * kstepB : cB;
;         for (int t = 0; t < nt; t += 2) {
;             const bool last = (t == nt - 2);
;             const char* a1 = cA + (size_t)(t + 1) * kstepA;
;             const char* a2 = last ? nA : cA + (size_t)(t + 2) * kstepA; const char* b2 = last ? nB : cB + (size_t)(t + 2) * kstepB;
;     ...
; #pragma unroll
;         for (int a = 0; a < 2; ++a)
; #pragma unroll
;             for (int b = 0; b < 2; ++b)
; #pragma unroll
;                 for (int m = 0; m < 4; ++m)
; #pragma unroll
;                     for (int n = 0; n < 2; ++n) acc[a][b][m][n] = (f32x4){0.f, 0.f, 0.f, 0.f};
.LBB0_1068:
	s_add_u32 s65, s34, 0x100
	s_addc_u32 s66, s35, 0
	s_add_u32 s34, s36, 0xc000
	v_mov_b32_e32 v2, 0
	s_addc_u32 s35, s37, 0
	s_mov_b32 s67, -2
	v_mov_b32_e32 v3, v2
	v_mov_b32_e32 v4, v2
	v_mov_b32_e32 v5, v2
	v_mov_b32_e32 v6, v2
	v_mov_b32_e32 v7, v2
	v_mov_b32_e32 v8, v2
	v_mov_b32_e32 v9, v2
	v_mov_b32_e32 v18, v2
	v_mov_b32_e32 v19, v2
	v_mov_b32_e32 v20, v2
	v_mov_b32_e32 v21, v2
	v_mov_b32_e32 v22, v2
	v_mov_b32_e32 v23, v2
	v_mov_b32_e32 v24, v2
	v_mov_b32_e32 v25, v2
	v_mov_b32_e32 v34, v2
	v_mov_b32_e32 v35, v2
	v_mov_b32_e32 v36, v2
	v_mov_b32_e32 v37, v2
	v_mov_b32_e32 v38, v2
	v_mov_b32_e32 v39, v2
	v_mov_b32_e32 v40, v2
	v_mov_b32_e32 v41, v2
	s_waitcnt vmcnt(0)
	v_mov_b32_e32 v50, v2
	v_mov_b32_e32 v51, v2
	v_mov_b32_e32 v52, v2
	v_mov_b32_e32 v53, v2
	v_mov_b32_e32 v54, v2
	v_mov_b32_e32 v55, v2
	v_mov_b32_e32 v56, v2
	v_mov_b32_e32 v57, v2
	v_mov_b32_e32 v10, v2
	v_mov_b32_e32 v11, v2
	v_mov_b32_e32 v12, v2
	v_mov_b32_e32 v13, v2
	v_mov_b32_e32 v14, v2
	v_mov_b32_e32 v15, v2
	v_mov_b32_e32 v16, v2
	v_mov_b32_e32 v17, v2
	v_mov_b32_e32 v26, v2
	v_mov_b32_e32 v27, v2
	v_mov_b32_e32 v28, v2
	v_mov_b32_e32 v29, v2
	v_mov_b32_e32 v30, v2
	v_mov_b32_e32 v31, v2
	v_mov_b32_e32 v32, v2
	v_mov_b32_e32 v33, v2
	v_mov_b32_e32 v42, v2
	v_mov_b32_e32 v43, v2
	v_mov_b32_e32 v44, v2
	v_mov_b32_e32 v45, v2
	v_mov_b32_e32 v46, v2
	v_mov_b32_e32 v47, v2
	v_mov_b32_e32 v48, v2
	v_mov_b32_e32 v49, v2
	v_mov_b32_e32 v58, v2
	v_mov_b32_e32 v59, v2
	v_mov_b32_e32 v60, v2
	v_mov_b32_e32 v61, v2
	v_mov_b32_e32 v62, v2
	v_mov_b32_e32 v63, v2
	v_mov_b32_e32 v64, v2
	v_mov_b32_e32 v65, v2
	v_mov_b32_e32 v66, v2
	v_mov_b32_e32 v67, v2
	v_mov_b32_e32 v68, v2
	v_mov_b32_e32 v69, v2
	v_mov_b32_e32 v70, v2
	v_mov_b32_e32 v71, v2
	v_mov_b32_e32 v72, v2
	v_mov_b32_e32 v73, v2
	v_mov_b32_e32 v82, v2
	v_mov_b32_e32 v83, v2
	v_mov_b32_e32 v84, v2
	v_mov_b32_e32 v85, v2
	v_mov_b32_e32 v86, v2
	v_mov_b32_e32 v87, v2
	v_mov_b32_e32 v88, v2
	v_mov_b32_e32 v89, v2
	v_mov_b32_e32 v98, v2
	v_mov_b32_e32 v99, v2
	v_mov_b32_e32 v100, v2
	v_mov_b32_e32 v101, v2
	v_mov_b32_e32 v102, v2
	v_mov_b32_e32 v103, v2
	v_mov_b32_e32 v104, v2
	v_mov_b32_e32 v105, v2
	v_mov_b32_e32 v114, v2
	v_mov_b32_e32 v115, v2
	v_mov_b32_e32 v116, v2
	v_mov_b32_e32 v117, v2
	v_mov_b32_e32 v118, v2
	v_mov_b32_e32 v119, v2
	v_mov_b32_e32 v120, v2
	v_mov_b32_e32 v121, v2
	v_mov_b32_e32 v74, v2
	v_mov_b32_e32 v75, v2
	v_mov_b32_e32 v76, v2
	v_mov_b32_e32 v77, v2
	v_mov_b32_e32 v78, v2
	v_mov_b32_e32 v79, v2
	v_mov_b32_e32 v80, v2
	v_mov_b32_e32 v81, v2
	v_mov_b32_e32 v90, v2
	v_mov_b32_e32 v91, v2
	v_mov_b32_e32 v92, v2
	v_mov_b32_e32 v93, v2
	v_mov_b32_e32 v94, v2
	v_mov_b32_e32 v95, v2
	v_mov_b32_e32 v96, v2
	v_mov_b32_e32 v97, v2
	v_mov_b32_e32 v106, v2
	v_mov_b32_e32 v107, v2
	v_mov_b32_e32 v108, v2
	v_mov_b32_e32 v109, v2
	v_mov_b32_e32 v110, v2
	v_mov_b32_e32 v111, v2
	v_mov_b32_e32 v112, v2
	v_mov_b32_e32 v113, v2
	v_mov_b32_e32 v122, v2
	v_mov_b32_e32 v123, v2
	v_mov_b32_e32 v124, v2
	v_mov_b32_e32 v125, v2
	v_mov_b32_e32 v126, v2
	v_mov_b32_e32 v127, v2
	v_mov_b32_e32 v128, v2
	v_mov_b32_e32 v129, v2
	.p2align	6

; template <class Epi, class Sched, bool ALIGN_EPI = false, bool SP2 = false, bool A_TILED = false, bool B_TILED = false>
; __device__ __forceinline__ void gemm_phase(PG8_LAS unsigned char* lds, const Gemm g, const Sched& S, const Epi& E) {
;     ...
;         const char* nA = has_next ? (const char*)g.A + (size_t)nxt.pm * tstep + (size_t)nxt.kt0 * kstepA : cA; const char* nB = has_next ? (const char*)g.Bt + (size_t)nxt.pn * tstep + (size_t)nxt.kt0 * kstepB : cB;
;         for (int t = 0; t < nt; t += 2) {
;             const bool last = (t == nt - 2);
;             const char* a1 = cA + (size_t)(t + 1) * kstepA;
;             const char* a2 = last ? nA : cA + (size_t)(t + 2) * kstepA; const char* b2 = last ? nB : cB + (size_t)(t + 2) * kstepB;
;     ...
; #pragma unroll
;         for (int a = 0; a < 2; ++a)
; #pragma unroll
;             for (int b = 0; b < 2; ++b)
; #pragma unroll
;                 for (int m = 0; m < 4; ++m)
; #pragma unroll
;                     for (int n = 0; n < 2; ++n) acc[a][b][m][n] = (f32x4){0.f, 0.f, 0.f, 0.f};
.LBB0_1096:
	s_add_i32 s17, s19, -2
	s_add_u32 s53, s24, 0x100
	s_addc_u32 s54, s25, 0
	s_add_u32 s24, s26, 0xc000
	v_mov_b32_e32 v0, 0
	s_addc_u32 s25, s27, 0
	s_mov_b32 s26, 0
	v_mov_b32_e32 v1, v0
	v_mov_b32_e32 v2, v0
	v_mov_b32_e32 v3, v0
	v_mov_b32_e32 v4, v0
	v_mov_b32_e32 v5, v0
	v_mov_b32_e32 v6, v0
	v_mov_b32_e32 v7, v0
	v_mov_b32_e32 v8, v0
	v_mov_b32_e32 v9, v0
	v_mov_b32_e32 v10, v0
	v_mov_b32_e32 v11, v0
	v_mov_b32_e32 v12, v0
	v_mov_b32_e32 v13, v0
	v_mov_b32_e32 v14, v0
	v_mov_b32_e32 v15, v0
	v_mov_b32_e32 v16, v0
	v_mov_b32_e32 v17, v0
	v_mov_b32_e32 v18, v0
	v_mov_b32_e32 v19, v0
	v_mov_b32_e32 v24, v0
	v_mov_b32_e32 v25, v0
	v_mov_b32_e32 v26, v0
	v_mov_b32_e32 v27, v0
	v_mov_b32_e32 v32, v0
	v_mov_b32_e32 v33, v0
	v_mov_b32_e32 v34, v0
	v_mov_b32_e32 v35, v0
	v_mov_b32_e32 v40, v0
	v_mov_b32_e32 v41, v0
	v_mov_b32_e32 v42, v0
	v_mov_b32_e32 v43, v0
	v_mov_b32_e32 v20, v0
	v_mov_b32_e32 v21, v0
	v_mov_b32_e32 v22, v0
	v_mov_b32_e32 v23, v0
	v_mov_b32_e32 v28, v0
	v_mov_b32_e32 v29, v0
	v_mov_b32_e32 v30, v0
	v_mov_b32_e32 v31, v0
	v_mov_b32_e32 v36, v0
	v_mov_b32_e32 v37, v0
	v_mov_b32_e32 v38, v0
	v_mov_b32_e32 v39, v0
	v_mov_b32_e32 v44, v0
	v_mov_b32_e32 v45, v0
	v_mov_b32_e32 v46, v0
	v_mov_b32_e32 v47, v0
	v_mov_b32_e32 v48, v0
	v_mov_b32_e32 v49, v0
	v_mov_b32_e32 v50, v0
	v_mov_b32_e32 v51, v0
	v_mov_b32_e32 v52, v0
	v_mov_b32_e32 v53, v0
	v_mov_b32_e32 v54, v0
	v_mov_b32_e32 v55, v0
	v_mov_b32_e32 v56, v0
	v_mov_b32_e32 v57, v0
	v_mov_b32_e32 v58, v0
	v_mov_b32_e32 v59, v0
	v_mov_b32_e32 v60, v0
	v_mov_b32_e32 v61, v0
	v_mov_b32_e32 v62, v0
	v_mov_b32_e32 v63, v0
	v_mov_b32_e32 v64, v0
	v_mov_b32_e32 v65, v0
	v_mov_b32_e32 v66, v0
	v_mov_b32_e32 v67, v0
	v_mov_b32_e32 v68, v0
	v_mov_b32_e32 v69, v0
	v_mov_b32_e32 v70, v0
	v_mov_b32_e32 v71, v0
	v_mov_b32_e32 v72, v0
	v_mov_b32_e32 v73, v0
	v_mov_b32_e32 v74, v0
	v_mov_b32_e32 v75, v0
	v_mov_b32_e32 v76, v0
	v_mov_b32_e32 v77, v0
	v_mov_b32_e32 v78, v0
	v_mov_b32_e32 v79, v0
	v_mov_b32_e32 v80, v0
	v_mov_b32_e32 v81, v0
	v_mov_b32_e32 v82, v0
	v_mov_b32_e32 v83, v0
	v_mov_b32_e32 v88, v0
	v_mov_b32_e32 v89, v0
	v_mov_b32_e32 v90, v0
	v_mov_b32_e32 v91, v0
	v_mov_b32_e32 v96, v0
	v_mov_b32_e32 v97, v0
	v_mov_b32_e32 v98, v0
	v_mov_b32_e32 v99, v0
	v_mov_b32_e32 v104, v0
	v_mov_b32_e32 v105, v0
	v_mov_b32_e32 v106, v0
	v_mov_b32_e32 v107, v0
	v_mov_b32_e32 v84, v0
	v_mov_b32_e32 v85, v0
	v_mov_b32_e32 v86, v0
	v_mov_b32_e32 v87, v0
	v_mov_b32_e32 v92, v0
	v_mov_b32_e32 v93, v0
	v_mov_b32_e32 v94, v0
	v_mov_b32_e32 v95, v0
	v_mov_b32_e32 v100, v0
	v_mov_b32_e32 v101, v0
	v_mov_b32_e32 v102, v0
	v_mov_b32_e32 v103, v0
	v_mov_b32_e32 v108, v0
	v_mov_b32_e32 v109, v0
	v_mov_b32_e32 v110, v0
	v_mov_b32_e32 v111, v0
	v_mov_b32_e32 v112, v0
	v_mov_b32_e32 v113, v0
	v_mov_b32_e32 v114, v0
	v_mov_b32_e32 v115, v0
	v_mov_b32_e32 v116, v0
	v_mov_b32_e32 v117, v0
	v_mov_b32_e32 v118, v0
	v_mov_b32_e32 v119, v0
	v_mov_b32_e32 v120, v0
	v_mov_b32_e32 v121, v0
	v_mov_b32_e32 v122, v0
	v_mov_b32_e32 v123, v0
	v_mov_b32_e32 v124, v0
	v_mov_b32_e32 v125, v0
	v_mov_b32_e32 v126, v0
	v_mov_b32_e32 v127, v0
	.p2align	6
